# combined: barrier shortcut + nmax LDS + p-tail + packed zeroing + P1 permlane reductions + P1 unit balance + flips deleted + pooling fast path
# speedup vs baseline: 1.0018x; 1.0018x over previous
;     __host__ __device__ bool next(int i, Unit& u) const { return i < cnt ? so.next(base + i, u) : false; }
;     __host__ __device__ bool next(int i, Unit& u) const { const int L = i * G + c; if (L >= 32) return false; u.g = L >> 3; u.pm = L & 7; u.pn = 0; return true; }
;   __device__ __forceinline__ bool next(int i,AttnUnit&u)const{ if(i>=4)return false; const int s=vcu&7; u.bh=vcu>>3; u.qb=(i==0)?s:(i==1)?15-s:(i==2)?16+s:31-s; return true; }
;     __host__ __device__ bool next(int i, Unit& u) const {
;     ...
;         int wgid = (int)L; { const int q = nwg / NXCD, r = nwg % NXCD, xcd = wgid % NXCD, off = wgid / NXCD; wgid = (xcd < r ? xcd * (q + 1) : r * (q + 1) + (xcd - r) * q) + off; }
;         const int nig = WGM * nN, gid = wgid / nig, fm = gid * WGM, gsz = (nM - fm) < WGM ? (nM - fm) : WGM;
;         u.pm = fm + ((wgid % nig) % gsz); u.pn = (wgid % nig) / gsz; u.g = 0; return true;
; template <class Epi, class Sched, bool ALIGN_EPI = false, bool SP2 = false>
; __device__ __forceinline__ void gemm_phase(PG8_LAS unsigned char* lds, const Gemm g, const Sched& S, const Epi& E) {
;     ...
;         const bool has_next = S.next(ui + 1, nxt);
;         const char* nA = has_next ? (const char*)(g.A + (size_t)nxt.g * g.gsA) + (size_t)nxt.pm * tstepA : cA; const char* nB = has_next ? (const char*)(g.Bt + (size_t)nxt.g * g.gsB) + (size_t)nxt.pn * tstepB : cB;
;         for (int t = 0; t < nt; t += 2) {
;             if constexpr (Epi::MIDK) { if (t == (nt >> 1)) { asm volatile("s_waitcnt vmcnt(0)" ::: "memory"); E.mid(acc, cur, wr, wc, fr, fq); asm volatile("s_waitcnt vmcnt(0)" ::: "memory"); } }
;             const bool last = (t == nt - 2);
;             const char* a1 = cA + (size_t)(t + 1) * kstep;
;             const char* a2 = last ? nA : cA + (size_t)(t + 2) * kstep; const char* b2 = last ? nB : cB + (size_t)(t + 2) * kstep;
;             const char* a3 = a2 + kstep; const char* b3 = b2 + kstep;
;     ...
; #pragma unroll
;         for (int a = 0; a < 2; ++a)
; #pragma unroll
;             for (int b = 0; b < 2; ++b)
; #pragma unroll
;                 for (int m = 0; m < 4; ++m)
; #pragma unroll
;                     for (int n = 0; n < 2; ++n) acc[a][b][m][n] = (f32x4){0.f, 0.f, 0.f, 0.f};
.LBB0_84:
	s_lshl_b32 s32, s63, 4
	s_and_b32 s32, s32, 16
	s_xor_b32 s22, s22, s32
	s_ashr_i32 s25, s24, 31
	s_lshl_b64 s[26:27], s[24:25], 20
	s_add_u32 s26, s37, s26
	s_addc_u32 s27, s38, s27
	s_ashr_i32 s23, s22, 31
	s_lshl_b64 s[28:29], s[22:23], 20
	s_add_u32 s28, s39, s28
	v_mov_b32_e32 v127, 0
	s_addc_u32 s29, s44, s29
	s_and_b64 vcc, exec, s[6:7]
	v_mov_b32_e32 v126, v127
	v_pk_mov_b32 v[124:125], v[126:127], v[126:127]
	v_pk_mov_b32 v[122:123], v[126:127], v[126:127]
	v_pk_mov_b32 v[120:121], v[126:127], v[126:127]
	v_pk_mov_b32 v[110:111], v[126:127], v[126:127]
	v_pk_mov_b32 v[108:109], v[126:127], v[126:127]
	v_pk_mov_b32 v[106:107], v[126:127], v[126:127]
	v_pk_mov_b32 v[104:105], v[126:127], v[126:127]
	v_pk_mov_b32 v[94:95], v[126:127], v[126:127]
	v_pk_mov_b32 v[92:93], v[126:127], v[126:127]
	v_pk_mov_b32 v[90:91], v[126:127], v[126:127]
	v_pk_mov_b32 v[88:89], v[126:127], v[126:127]
	v_pk_mov_b32 v[78:79], v[126:127], v[126:127]
	v_pk_mov_b32 v[76:77], v[126:127], v[126:127]
	v_pk_mov_b32 v[74:75], v[126:127], v[126:127]
	v_pk_mov_b32 v[72:73], v[126:127], v[126:127]
	v_pk_mov_b32 v[118:119], v[126:127], v[126:127]
	v_pk_mov_b32 v[116:117], v[126:127], v[126:127]
	v_pk_mov_b32 v[114:115], v[126:127], v[126:127]
	v_pk_mov_b32 v[112:113], v[126:127], v[126:127]
	v_pk_mov_b32 v[102:103], v[126:127], v[126:127]
	v_pk_mov_b32 v[100:101], v[126:127], v[126:127]
	v_pk_mov_b32 v[98:99], v[126:127], v[126:127]
	v_pk_mov_b32 v[96:97], v[126:127], v[126:127]
	v_pk_mov_b32 v[86:87], v[126:127], v[126:127]
	v_pk_mov_b32 v[84:85], v[126:127], v[126:127]
	v_pk_mov_b32 v[82:83], v[126:127], v[126:127]
	v_pk_mov_b32 v[80:81], v[126:127], v[126:127]
	v_pk_mov_b32 v[70:71], v[126:127], v[126:127]
	v_pk_mov_b32 v[68:69], v[126:127], v[126:127]
	v_pk_mov_b32 v[66:67], v[126:127], v[126:127]
	v_pk_mov_b32 v[64:65], v[126:127], v[126:127]
	v_pk_mov_b32 v[62:63], v[126:127], v[126:127]
	v_pk_mov_b32 v[60:61], v[126:127], v[126:127]
	v_pk_mov_b32 v[58:59], v[126:127], v[126:127]
	v_pk_mov_b32 v[56:57], v[126:127], v[126:127]
	v_pk_mov_b32 v[46:47], v[126:127], v[126:127]
	v_pk_mov_b32 v[44:45], v[126:127], v[126:127]
	v_pk_mov_b32 v[42:43], v[126:127], v[126:127]
	v_pk_mov_b32 v[40:41], v[126:127], v[126:127]
	v_pk_mov_b32 v[30:31], v[126:127], v[126:127]
	v_pk_mov_b32 v[28:29], v[126:127], v[126:127]
	v_pk_mov_b32 v[26:27], v[126:127], v[126:127]
	v_pk_mov_b32 v[24:25], v[126:127], v[126:127]
	v_pk_mov_b32 v[14:15], v[126:127], v[126:127]
	v_pk_mov_b32 v[12:13], v[126:127], v[126:127]
	v_pk_mov_b32 v[10:11], v[126:127], v[126:127]
	v_pk_mov_b32 v[8:9], v[126:127], v[126:127]
	v_pk_mov_b32 v[54:55], v[126:127], v[126:127]
	v_pk_mov_b32 v[52:53], v[126:127], v[126:127]
	v_pk_mov_b32 v[50:51], v[126:127], v[126:127]
	v_pk_mov_b32 v[48:49], v[126:127], v[126:127]
	v_pk_mov_b32 v[38:39], v[126:127], v[126:127]
	v_pk_mov_b32 v[36:37], v[126:127], v[126:127]
	v_pk_mov_b32 v[34:35], v[126:127], v[126:127]
	v_pk_mov_b32 v[32:33], v[126:127], v[126:127]
	v_pk_mov_b32 v[22:23], v[126:127], v[126:127]
	v_pk_mov_b32 v[20:21], v[126:127], v[126:127]
	v_pk_mov_b32 v[18:19], v[126:127], v[126:127]
	v_pk_mov_b32 v[16:17], v[126:127], v[126:127]
	v_pk_mov_b32 v[6:7], v[126:127], v[126:127]
	v_pk_mov_b32 v[4:5], v[126:127], v[126:127]
	v_pk_mov_b32 v[2:3], v[126:127], v[126:127]
	s_waitcnt lgkmcnt(0)
	v_pk_mov_b32 v[0:1], v[126:127], v[126:127]
	s_cbranch_vccnz .LBB0_87
	s_and_b64 s[34:35], s[8:9], exec
	s_cselect_b32 s11, s27, s31
	s_cselect_b32 s23, s26, s30
	s_cselect_b32 s25, s29, s13
	s_cselect_b32 s40, s28, s12
	s_add_u32 s41, s12, 0x100
	s_addc_u32 s42, s13, 0
	s_add_u32 s12, s30, 0x80080
	s_addc_u32 s13, s31, 0
	s_mov_b32 s30, 0
